# nt hint on read-once residual-stream (xi) epilogue loads in P5/P7
# speedup vs baseline: 1.0011x; 1.0011x over previous
.LBB0_616:
	global_load_dwordx4 v[136:139], v[182:183], off offset:512 nt
	s_nop 0
	global_load_dwordx4 v[140:143], v[182:183], off offset:528 nt
	s_and_b64 vcc, exec, s[8:9]
	s_waitcnt vmcnt(1)
	v_pk_fma_f32 v[134:135], v[134:135], v[70:71], v[138:139]
	v_pk_fma_f32 v[132:133], v[132:133], v[68:69], v[136:137]
	s_waitcnt vmcnt(0)
	v_pk_fma_f32 v[130:131], v[130:131], v[82:83], v[142:143]
	v_pk_fma_f32 v[128:129], v[128:129], v[80:81], v[140:141]
	global_store_dwordx4 v[184:185], v[132:135], off offset:512
	global_store_dwordx4 v[184:185], v[128:131], off offset:528
	s_cbranch_vccnz .LBB0_620
	v_pk_mul_f32 v[142:143], v[172:173], v[130:131]
	v_mul_f32_e32 v131, v131, v131
	v_fmac_f32_e32 v131, v130, v130
	v_mul_f32_e32 v130, v133, v133
	v_pk_mul_f32 v[136:137], v[158:159], v[132:133]
	v_fmac_f32_e32 v130, v132, v132
	v_mul_f32_e32 v132, v135, v135
	v_pk_mul_f32 v[162:163], v[156:157], v[128:129]
	v_fmac_f32_e32 v132, v134, v134
	v_mul_f32_e32 v129, v129, v129
	v_add_f32_e32 v130, v130, v132
	v_fmac_f32_e32 v129, v128, v128
	v_add_f32_e32 v128, v130, v129
	v_add_f32_e32 v128, v131, v128
	v_add_f32_e32 v130, v190, v128
	ds_swizzle_b32 v131, v130 offset:swizzle(SWAP,16)
	v_lshlrev_b64 v[140:141], 1, v[180:181]
	v_or_b32_e32 v140, 0x100, v140
	v_pk_mul_f32 v[138:139], v[166:167], v[134:135]
	v_lshl_add_u64 v[128:129], s[44:45], 0, v[140:141]
	v_cvt_pk_bf16_f32 v136, v136, v137
	v_cvt_pk_bf16_f32 v137, v138, v139
	v_cvt_pk_bf16_f32 v138, v162, v163
	v_cvt_pk_bf16_f32 v139, v142, v143
	global_store_dwordx4 v[128:129], v[136:139], off
	s_waitcnt lgkmcnt(0)
	v_add_f32_e32 v128, v130, v131
	v_mov_b32_e32 v129, v128
	s_nop 1
	v_permlane32_swap_b32_e32 v128, v129
	s_and_saveexec_b64 s[26:27], s[4:5]
	s_cbranch_execz .LBB0_619
	v_lshl_add_u64 v[130:131], v[178:179], 2, s[50:51]
	v_add_f32_e32 v128, v128, v129
	global_atomic_add_f32 v[130:131], v128, off

.LBB0_620:
	s_nop 0
	v_or_b32_e32 v128, 16, v178
	v_ashrrev_i32_e32 v129, 31, v128
	v_lshlrev_b64 v[130:131], 10, v[128:129]
	v_lshl_add_u64 v[130:131], v[130:131], 0, v[176:177]
	v_lshlrev_b64 v[134:135], 2, v[130:131]
	v_lshl_add_u64 v[132:133], s[10:11], 0, v[134:135]
	global_load_dwordx4 v[136:139], v[132:133], off nt
	global_load_dwordx4 v[140:143], v[132:133], off offset:16 nt
	s_and_b64 vcc, exec, s[8:9]
	v_lshl_add_u64 v[134:135], s[72:73], 0, v[134:135]
	s_waitcnt vmcnt(1)
	v_pk_fma_f32 v[126:127], v[126:127], v[78:79], v[138:139]
	v_pk_fma_f32 v[124:125], v[124:125], v[76:77], v[136:137]
	s_waitcnt vmcnt(0)
	v_pk_fma_f32 v[122:123], v[122:123], v[86:87], v[142:143]
	v_pk_fma_f32 v[120:121], v[120:121], v[84:85], v[140:141]
	v_mov_b32_e32 v136, 0
	global_store_dwordx4 v[134:135], v[124:127], off
	global_store_dwordx4 v[134:135], v[120:123], off offset:16
	s_cbranch_vccnz .LBB0_622
	v_pk_mul_f32 v[136:137], v[126:127], v[126:127]
	v_pk_mul_f32 v[138:139], v[124:125], v[124:125]
	v_pk_mul_f32 v[124:125], v[168:169], v[124:125]
	v_pk_mov_b32 v[140:141], v[138:139], v[136:137] op_sel:[1,0]
	v_mov_b32_e32 v139, v137
	v_pk_add_f32 v[136:137], v[140:141], v[138:139]
	v_pk_mul_f32 v[138:139], v[122:123], v[122:123]
	v_pk_mul_f32 v[140:141], v[120:121], v[120:121]
	v_mov_b32_e32 v142, v138
	v_mov_b32_e32 v143, v140
	v_mov_b32_e32 v140, v139
	v_pk_add_f32 v[138:139], v[142:143], v[140:141]
	v_add_f32_e32 v136, v136, v137
	v_add_f32_e32 v136, v136, v139
	v_add_f32_e32 v136, v138, v136
	v_pk_mul_f32 v[138:139], v[174:175], v[122:123]
	v_pk_mul_f32 v[122:123], v[154:155], v[120:121]
	v_cvt_pk_bf16_f32 v120, v124, v125
	v_lshl_add_u64 v[124:125], v[130:131], 1, s[44:45]
	v_pk_mul_f32 v[126:127], v[170:171], v[126:127]
	s_nop 0
	v_cvt_pk_bf16_f32 v121, v126, v127
	v_cvt_pk_bf16_f32 v122, v122, v123
	v_cvt_pk_bf16_f32 v123, v138, v139
	global_store_dwordx4 v[124:125], v[120:123], off
.LBB0_622:
	global_load_dwordx4 v[120:123], v[132:133], off offset:512 nt
	s_nop 0
	global_load_dwordx4 v[124:127], v[132:133], off offset:528 nt
	s_and_b64 vcc, exec, s[8:9]
	s_waitcnt vmcnt(1)
	v_pk_fma_f32 v[118:119], v[118:119], v[70:71], v[122:123]
	v_pk_fma_f32 v[116:117], v[116:117], v[68:69], v[120:121]
	s_waitcnt vmcnt(0)
	v_pk_fma_f32 v[114:115], v[114:115], v[82:83], v[126:127]
	v_pk_fma_f32 v[112:113], v[112:113], v[80:81], v[124:125]
	global_store_dwordx4 v[134:135], v[116:119], off offset:512
	global_store_dwordx4 v[134:135], v[112:115], off offset:528
	s_cbranch_vccnz .LBB0_626
	v_pk_mul_f32 v[126:127], v[172:173], v[114:115]
	v_mul_f32_e32 v115, v115, v115
	v_fmac_f32_e32 v115, v114, v114
	v_mul_f32_e32 v114, v117, v117
	v_pk_mul_f32 v[120:121], v[158:159], v[116:117]
	v_fmac_f32_e32 v114, v116, v116
	v_mul_f32_e32 v116, v119, v119
	v_lshlrev_b64 v[124:125], 1, v[130:131]
	v_pk_mul_f32 v[130:131], v[156:157], v[112:113]
	v_fmac_f32_e32 v116, v118, v118
	v_mul_f32_e32 v113, v113, v113
	v_add_f32_e32 v114, v114, v116
	v_fmac_f32_e32 v113, v112, v112
	v_add_f32_e32 v112, v114, v113
	v_add_f32_e32 v112, v115, v112
	v_add_f32_e32 v114, v136, v112
	ds_swizzle_b32 v115, v114 offset:swizzle(SWAP,16)
	v_or_b32_e32 v124, 0x100, v124
	v_pk_mul_f32 v[122:123], v[166:167], v[118:119]
	v_lshl_add_u64 v[112:113], s[44:45], 0, v[124:125]
	v_cvt_pk_bf16_f32 v120, v120, v121
	v_cvt_pk_bf16_f32 v121, v122, v123
	v_cvt_pk_bf16_f32 v122, v130, v131
	v_cvt_pk_bf16_f32 v123, v126, v127
	global_store_dwordx4 v[112:113], v[120:123], off
	s_waitcnt lgkmcnt(0)
	v_add_f32_e32 v112, v114, v115
	v_mov_b32_e32 v113, v112
	s_nop 1
	v_permlane32_swap_b32_e32 v112, v113
	s_and_saveexec_b64 s[26:27], s[4:5]
	s_cbranch_execz .LBB0_625
	v_lshl_add_u64 v[114:115], v[128:129], 2, s[50:51]
	v_add_f32_e32 v112, v112, v113
	global_atomic_add_f32 v[114:115], v112, off

.LBB0_626:
	s_nop 0
	v_or_b32_e32 v112, 32, v178
	v_ashrrev_i32_e32 v113, 31, v112
	v_lshlrev_b64 v[114:115], 10, v[112:113]
	v_lshl_add_u64 v[114:115], v[114:115], 0, v[176:177]
	v_lshlrev_b64 v[118:119], 2, v[114:115]
	v_lshl_add_u64 v[116:117], s[10:11], 0, v[118:119]
	global_load_dwordx4 v[120:123], v[116:117], off nt
	global_load_dwordx4 v[124:127], v[116:117], off offset:16 nt
	s_and_b64 vcc, exec, s[8:9]
	v_lshl_add_u64 v[118:119], s[72:73], 0, v[118:119]
	s_waitcnt vmcnt(1)
	v_pk_fma_f32 v[110:111], v[110:111], v[78:79], v[122:123]
	v_pk_fma_f32 v[108:109], v[108:109], v[76:77], v[120:121]
	s_waitcnt vmcnt(0)
	v_pk_fma_f32 v[106:107], v[106:107], v[86:87], v[126:127]
	v_pk_fma_f32 v[104:105], v[104:105], v[84:85], v[124:125]
	v_mov_b32_e32 v120, 0
	global_store_dwordx4 v[118:119], v[108:111], off
	global_store_dwordx4 v[118:119], v[104:107], off offset:16
	s_cbranch_vccnz .LBB0_628
	v_pk_mul_f32 v[120:121], v[110:111], v[110:111]
	v_pk_mul_f32 v[122:123], v[108:109], v[108:109]
	v_pk_mul_f32 v[108:109], v[168:169], v[108:109]
	v_pk_mov_b32 v[124:125], v[122:123], v[120:121] op_sel:[1,0]
	v_mov_b32_e32 v123, v121
	v_pk_add_f32 v[120:121], v[124:125], v[122:123]
	v_pk_mul_f32 v[122:123], v[106:107], v[106:107]
	v_pk_mul_f32 v[124:125], v[104:105], v[104:105]
	v_mov_b32_e32 v126, v122
	v_mov_b32_e32 v127, v124
	v_mov_b32_e32 v124, v123
	v_pk_add_f32 v[122:123], v[126:127], v[124:125]
	v_add_f32_e32 v120, v120, v121
	v_add_f32_e32 v120, v120, v123
	v_add_f32_e32 v120, v122, v120
	v_pk_mul_f32 v[122:123], v[174:175], v[106:107]
	v_pk_mul_f32 v[106:107], v[154:155], v[104:105]
	v_cvt_pk_bf16_f32 v104, v108, v109
	v_lshl_add_u64 v[108:109], v[114:115], 1, s[44:45]
	v_pk_mul_f32 v[110:111], v[170:171], v[110:111]
	s_nop 0
	v_cvt_pk_bf16_f32 v105, v110, v111
	v_cvt_pk_bf16_f32 v106, v106, v107
	v_cvt_pk_bf16_f32 v107, v122, v123
	global_store_dwordx4 v[108:109], v[104:107], off
.LBB0_628:
	global_load_dwordx4 v[104:107], v[116:117], off offset:512 nt
	s_nop 0
	global_load_dwordx4 v[108:111], v[116:117], off offset:528 nt
	s_and_b64 vcc, exec, s[8:9]
	s_waitcnt vmcnt(1)
	v_pk_fma_f32 v[102:103], v[102:103], v[70:71], v[106:107]
	v_pk_fma_f32 v[100:101], v[100:101], v[68:69], v[104:105]
	s_waitcnt vmcnt(0)
	v_pk_fma_f32 v[98:99], v[98:99], v[82:83], v[110:111]
	v_pk_fma_f32 v[96:97], v[96:97], v[80:81], v[108:109]
	global_store_dwordx4 v[118:119], v[100:103], off offset:512
	global_store_dwordx4 v[118:119], v[96:99], off offset:528
	s_cbranch_vccnz .LBB0_632
	v_pk_mul_f32 v[110:111], v[172:173], v[98:99]
	v_mul_f32_e32 v99, v99, v99
	v_fmac_f32_e32 v99, v98, v98
	v_mul_f32_e32 v98, v101, v101
	v_pk_mul_f32 v[104:105], v[158:159], v[100:101]
	v_fmac_f32_e32 v98, v100, v100
	v_mul_f32_e32 v100, v103, v103
	v_lshlrev_b64 v[108:109], 1, v[114:115]
	v_pk_mul_f32 v[114:115], v[156:157], v[96:97]
	v_fmac_f32_e32 v100, v102, v102
	v_mul_f32_e32 v97, v97, v97
	v_add_f32_e32 v98, v98, v100
	v_fmac_f32_e32 v97, v96, v96
	v_add_f32_e32 v96, v98, v97
	v_add_f32_e32 v96, v99, v96
	v_add_f32_e32 v98, v120, v96
	ds_swizzle_b32 v99, v98 offset:swizzle(SWAP,16)
	v_or_b32_e32 v108, 0x100, v108
	v_pk_mul_f32 v[106:107], v[166:167], v[102:103]
	v_lshl_add_u64 v[96:97], s[44:45], 0, v[108:109]
	v_cvt_pk_bf16_f32 v104, v104, v105
	v_cvt_pk_bf16_f32 v105, v106, v107
	v_cvt_pk_bf16_f32 v106, v114, v115
	v_cvt_pk_bf16_f32 v107, v110, v111
	global_store_dwordx4 v[96:97], v[104:107], off
	s_waitcnt lgkmcnt(0)
	v_add_f32_e32 v96, v98, v99
	v_mov_b32_e32 v97, v96
	s_nop 1
	v_permlane32_swap_b32_e32 v96, v97
	s_and_saveexec_b64 s[26:27], s[4:5]
	s_cbranch_execz .LBB0_631
	v_lshl_add_u64 v[98:99], v[112:113], 2, s[50:51]
	v_add_f32_e32 v96, v96, v97
	global_atomic_add_f32 v[98:99], v96, off

.LBB0_632:
	s_nop 0
	v_or_b32_e32 v96, 48, v178
	v_ashrrev_i32_e32 v97, 31, v96
	v_lshlrev_b64 v[98:99], 10, v[96:97]
	v_lshl_add_u64 v[98:99], v[98:99], 0, v[176:177]
	v_lshlrev_b64 v[102:103], 2, v[98:99]
	v_lshl_add_u64 v[100:101], s[10:11], 0, v[102:103]
	global_load_dwordx4 v[104:107], v[100:101], off nt
	global_load_dwordx4 v[108:111], v[100:101], off offset:16 nt
	s_and_b64 vcc, exec, s[8:9]
	v_lshl_add_u64 v[102:103], s[72:73], 0, v[102:103]
	s_waitcnt vmcnt(1)
	v_pk_fma_f32 v[94:95], v[94:95], v[78:79], v[106:107]
	v_pk_fma_f32 v[92:93], v[92:93], v[76:77], v[104:105]
	s_waitcnt vmcnt(0)
	v_pk_fma_f32 v[90:91], v[90:91], v[86:87], v[110:111]
	v_pk_fma_f32 v[88:89], v[88:89], v[84:85], v[108:109]
	v_mov_b32_e32 v104, 0
	global_store_dwordx4 v[102:103], v[92:95], off
	global_store_dwordx4 v[102:103], v[88:91], off offset:16
	s_cbranch_vccnz .LBB0_634
	v_pk_mul_f32 v[104:105], v[94:95], v[94:95]
	v_pk_mul_f32 v[106:107], v[92:93], v[92:93]
	v_pk_mul_f32 v[92:93], v[168:169], v[92:93]
	v_pk_mov_b32 v[108:109], v[106:107], v[104:105] op_sel:[1,0]
	v_mov_b32_e32 v107, v105
	v_pk_add_f32 v[104:105], v[108:109], v[106:107]
	v_pk_mul_f32 v[106:107], v[90:91], v[90:91]
	v_pk_mul_f32 v[108:109], v[88:89], v[88:89]
	v_mov_b32_e32 v110, v106
	v_mov_b32_e32 v111, v108
	v_mov_b32_e32 v108, v107
	v_pk_add_f32 v[106:107], v[110:111], v[108:109]
	v_add_f32_e32 v104, v104, v105
	v_add_f32_e32 v104, v104, v107
	v_add_f32_e32 v104, v106, v104
	v_pk_mul_f32 v[106:107], v[174:175], v[90:91]
	v_pk_mul_f32 v[90:91], v[154:155], v[88:89]
	v_cvt_pk_bf16_f32 v88, v92, v93
	v_lshl_add_u64 v[92:93], v[98:99], 1, s[44:45]
	v_pk_mul_f32 v[94:95], v[170:171], v[94:95]
	s_nop 0
	v_cvt_pk_bf16_f32 v89, v94, v95
	v_cvt_pk_bf16_f32 v90, v90, v91
	v_cvt_pk_bf16_f32 v91, v106, v107
	global_store_dwordx4 v[92:93], v[88:91], off
.LBB0_634:
	global_load_dwordx4 v[88:91], v[100:101], off offset:512 nt
	s_nop 0
	global_load_dwordx4 v[92:95], v[100:101], off offset:528 nt
	s_and_b64 vcc, exec, s[8:9]
	s_waitcnt vmcnt(1)
	v_pk_fma_f32 v[74:75], v[74:75], v[70:71], v[90:91]
	v_pk_fma_f32 v[72:73], v[72:73], v[68:69], v[88:89]
	s_waitcnt vmcnt(0)
	v_pk_fma_f32 v[66:67], v[66:67], v[82:83], v[94:95]
	v_pk_fma_f32 v[64:65], v[64:65], v[80:81], v[92:93]
	global_store_dwordx4 v[102:103], v[72:75], off offset:512
	global_store_dwordx4 v[102:103], v[64:67], off offset:528
	s_cbranch_vccnz .LBB0_638
	v_pk_mul_f32 v[94:95], v[172:173], v[66:67]
	v_mul_f32_e32 v67, v67, v67
	v_fmac_f32_e32 v67, v66, v66
	v_mul_f32_e32 v66, v73, v73
	v_pk_mul_f32 v[88:89], v[158:159], v[72:73]
	v_fmac_f32_e32 v66, v72, v72
	v_mul_f32_e32 v72, v75, v75
	v_lshlrev_b64 v[92:93], 1, v[98:99]
	v_pk_mul_f32 v[98:99], v[156:157], v[64:65]
	v_fmac_f32_e32 v72, v74, v74
	v_mul_f32_e32 v65, v65, v65
	v_add_f32_e32 v66, v66, v72
	v_fmac_f32_e32 v65, v64, v64
	v_add_f32_e32 v64, v66, v65
	v_add_f32_e32 v64, v67, v64
	v_add_f32_e32 v66, v104, v64
	ds_swizzle_b32 v67, v66 offset:swizzle(SWAP,16)
	v_or_b32_e32 v92, 0x100, v92
	v_pk_mul_f32 v[90:91], v[166:167], v[74:75]
	v_lshl_add_u64 v[64:65], s[44:45], 0, v[92:93]
	v_cvt_pk_bf16_f32 v88, v88, v89
	v_cvt_pk_bf16_f32 v89, v90, v91
	v_cvt_pk_bf16_f32 v90, v98, v99
	v_cvt_pk_bf16_f32 v91, v94, v95
	global_store_dwordx4 v[64:65], v[88:91], off
	s_waitcnt lgkmcnt(0)
	v_add_f32_e32 v64, v66, v67
	v_mov_b32_e32 v65, v64
	s_nop 1
	v_permlane32_swap_b32_e32 v64, v65
	s_and_saveexec_b64 s[26:27], s[4:5]
	s_cbranch_execz .LBB0_637
	v_lshl_add_u64 v[66:67], v[96:97], 2, s[50:51]
	v_add_f32_e32 v64, v64, v65
	global_atomic_add_f32 v[66:67], v64, off

.LBB0_638:
	s_nop 0
	v_add_u32_e32 v64, 0x80, v178
	v_ashrrev_i32_e32 v65, 31, v64
	v_lshlrev_b64 v[66:67], 10, v[64:65]
	v_lshl_add_u64 v[66:67], v[66:67], 0, v[176:177]
	v_lshlrev_b64 v[74:75], 2, v[66:67]
	v_lshl_add_u64 v[72:73], s[10:11], 0, v[74:75]
	global_load_dwordx4 v[88:91], v[72:73], off nt
	global_load_dwordx4 v[92:95], v[72:73], off offset:16 nt
	s_and_b64 vcc, exec, s[8:9]
	v_lshl_add_u64 v[74:75], s[72:73], 0, v[74:75]
	s_waitcnt vmcnt(1)
	v_pk_fma_f32 v[62:63], v[62:63], v[78:79], v[90:91]
	v_pk_fma_f32 v[60:61], v[60:61], v[76:77], v[88:89]
	s_waitcnt vmcnt(0)
	v_pk_fma_f32 v[58:59], v[58:59], v[86:87], v[94:95]
	v_pk_fma_f32 v[56:57], v[56:57], v[84:85], v[92:93]
	v_mov_b32_e32 v88, 0
	global_store_dwordx4 v[74:75], v[60:63], off
	global_store_dwordx4 v[74:75], v[56:59], off offset:16
	s_cbranch_vccnz .LBB0_640
	v_pk_mul_f32 v[88:89], v[62:63], v[62:63]
	v_pk_mul_f32 v[90:91], v[60:61], v[60:61]
	v_pk_mul_f32 v[60:61], v[168:169], v[60:61]
	v_pk_mov_b32 v[92:93], v[90:91], v[88:89] op_sel:[1,0]
	v_mov_b32_e32 v91, v89
	v_pk_add_f32 v[88:89], v[92:93], v[90:91]
	v_pk_mul_f32 v[90:91], v[58:59], v[58:59]
	v_pk_mul_f32 v[92:93], v[56:57], v[56:57]
	v_mov_b32_e32 v94, v90
	v_mov_b32_e32 v95, v92
	v_mov_b32_e32 v92, v91
	v_pk_add_f32 v[90:91], v[94:95], v[92:93]
	v_add_f32_e32 v88, v88, v89
	v_add_f32_e32 v88, v88, v91
	v_add_f32_e32 v88, v90, v88
	v_pk_mul_f32 v[90:91], v[174:175], v[58:59]
	v_pk_mul_f32 v[58:59], v[154:155], v[56:57]
	v_cvt_pk_bf16_f32 v56, v60, v61
	v_lshl_add_u64 v[60:61], v[66:67], 1, s[44:45]
	v_pk_mul_f32 v[62:63], v[170:171], v[62:63]
	s_nop 0
	v_cvt_pk_bf16_f32 v57, v62, v63
	v_cvt_pk_bf16_f32 v58, v58, v59
	v_cvt_pk_bf16_f32 v59, v90, v91
	global_store_dwordx4 v[60:61], v[56:59], off
.LBB0_640:
	global_load_dwordx4 v[56:59], v[72:73], off offset:512 nt
	s_nop 0
	global_load_dwordx4 v[60:63], v[72:73], off offset:528 nt
	s_and_b64 vcc, exec, s[8:9]
	s_waitcnt vmcnt(1)
	v_pk_fma_f32 v[54:55], v[54:55], v[70:71], v[58:59]
	v_pk_fma_f32 v[52:53], v[52:53], v[68:69], v[56:57]
	s_waitcnt vmcnt(0)
	v_pk_fma_f32 v[50:51], v[50:51], v[82:83], v[62:63]
	v_pk_fma_f32 v[48:49], v[48:49], v[80:81], v[60:61]
	global_store_dwordx4 v[74:75], v[52:55], off offset:512
	global_store_dwordx4 v[74:75], v[48:51], off offset:528
	s_cbranch_vccnz .LBB0_644
	v_pk_mul_f32 v[62:63], v[172:173], v[50:51]
	v_mul_f32_e32 v51, v51, v51
	v_fmac_f32_e32 v51, v50, v50
	v_mul_f32_e32 v50, v53, v53
	v_pk_mul_f32 v[56:57], v[158:159], v[52:53]
	v_fmac_f32_e32 v50, v52, v52
	v_mul_f32_e32 v52, v55, v55
	v_lshlrev_b64 v[60:61], 1, v[66:67]
	v_pk_mul_f32 v[66:67], v[156:157], v[48:49]
	v_fmac_f32_e32 v52, v54, v54
	v_mul_f32_e32 v49, v49, v49
	v_add_f32_e32 v50, v50, v52
	v_fmac_f32_e32 v49, v48, v48
	v_add_f32_e32 v48, v50, v49
	v_add_f32_e32 v48, v51, v48
	v_add_f32_e32 v50, v88, v48
	ds_swizzle_b32 v51, v50 offset:swizzle(SWAP,16)
	v_or_b32_e32 v60, 0x100, v60
	v_pk_mul_f32 v[58:59], v[166:167], v[54:55]
	v_lshl_add_u64 v[48:49], s[44:45], 0, v[60:61]
	v_cvt_pk_bf16_f32 v56, v56, v57
	v_cvt_pk_bf16_f32 v57, v58, v59
	v_cvt_pk_bf16_f32 v58, v66, v67
	v_cvt_pk_bf16_f32 v59, v62, v63
	global_store_dwordx4 v[48:49], v[56:59], off
	s_waitcnt lgkmcnt(0)
	v_add_f32_e32 v48, v50, v51
	v_mov_b32_e32 v49, v48
	s_nop 1
	v_permlane32_swap_b32_e32 v48, v49
	s_and_saveexec_b64 s[26:27], s[4:5]
	s_cbranch_execz .LBB0_643
	v_lshl_add_u64 v[50:51], v[64:65], 2, s[50:51]
	v_add_f32_e32 v48, v48, v49
	global_atomic_add_f32 v[50:51], v48, off

.LBB0_644:
	s_nop 0
	v_add_u32_e32 v48, 0x90, v178
	v_ashrrev_i32_e32 v49, 31, v48
	v_lshlrev_b64 v[50:51], 10, v[48:49]
	v_lshl_add_u64 v[50:51], v[50:51], 0, v[176:177]
	v_lshlrev_b64 v[54:55], 2, v[50:51]
	v_lshl_add_u64 v[52:53], s[10:11], 0, v[54:55]
	global_load_dwordx4 v[56:59], v[52:53], off nt
	global_load_dwordx4 v[60:63], v[52:53], off offset:16 nt
	s_and_b64 vcc, exec, s[8:9]
	v_lshl_add_u64 v[54:55], s[72:73], 0, v[54:55]
	s_waitcnt vmcnt(1)
	v_pk_fma_f32 v[46:47], v[46:47], v[78:79], v[58:59]
	v_pk_fma_f32 v[44:45], v[44:45], v[76:77], v[56:57]
	s_waitcnt vmcnt(0)
	v_pk_fma_f32 v[42:43], v[42:43], v[86:87], v[62:63]
	v_pk_fma_f32 v[40:41], v[40:41], v[84:85], v[60:61]
	v_mov_b32_e32 v56, 0
	global_store_dwordx4 v[54:55], v[44:47], off
	global_store_dwordx4 v[54:55], v[40:43], off offset:16
	s_cbranch_vccnz .LBB0_646
	v_pk_mul_f32 v[56:57], v[46:47], v[46:47]
	v_pk_mul_f32 v[58:59], v[44:45], v[44:45]
	v_pk_mul_f32 v[44:45], v[168:169], v[44:45]
	v_pk_mov_b32 v[60:61], v[58:59], v[56:57] op_sel:[1,0]
	v_mov_b32_e32 v59, v57
	v_pk_add_f32 v[56:57], v[60:61], v[58:59]
	v_pk_mul_f32 v[58:59], v[42:43], v[42:43]
	v_pk_mul_f32 v[60:61], v[40:41], v[40:41]
	v_mov_b32_e32 v62, v58
	v_mov_b32_e32 v63, v60
	v_mov_b32_e32 v60, v59
	v_pk_add_f32 v[58:59], v[62:63], v[60:61]
	v_add_f32_e32 v56, v56, v57
	v_add_f32_e32 v56, v56, v59
	v_add_f32_e32 v56, v58, v56
	v_pk_mul_f32 v[58:59], v[174:175], v[42:43]
	v_pk_mul_f32 v[42:43], v[154:155], v[40:41]
	v_cvt_pk_bf16_f32 v40, v44, v45
	v_lshl_add_u64 v[44:45], v[50:51], 1, s[44:45]
	v_pk_mul_f32 v[46:47], v[170:171], v[46:47]
	s_nop 0
	v_cvt_pk_bf16_f32 v41, v46, v47
	v_cvt_pk_bf16_f32 v42, v42, v43
	v_cvt_pk_bf16_f32 v43, v58, v59
	global_store_dwordx4 v[44:45], v[40:43], off
.LBB0_646:
	global_load_dwordx4 v[40:43], v[52:53], off offset:512 nt
	s_nop 0
	global_load_dwordx4 v[44:47], v[52:53], off offset:528 nt
	s_and_b64 vcc, exec, s[8:9]
	s_waitcnt vmcnt(1)
	v_pk_fma_f32 v[38:39], v[38:39], v[70:71], v[42:43]
	v_pk_fma_f32 v[36:37], v[36:37], v[68:69], v[40:41]
	s_waitcnt vmcnt(0)
	v_pk_fma_f32 v[34:35], v[34:35], v[82:83], v[46:47]
	v_pk_fma_f32 v[32:33], v[32:33], v[80:81], v[44:45]
	global_store_dwordx4 v[54:55], v[36:39], off offset:512
	global_store_dwordx4 v[54:55], v[32:35], off offset:528
	s_cbranch_vccnz .LBB0_650
	v_pk_mul_f32 v[46:47], v[172:173], v[34:35]
	v_mul_f32_e32 v35, v35, v35
	v_fmac_f32_e32 v35, v34, v34
	v_mul_f32_e32 v34, v37, v37
	v_pk_mul_f32 v[40:41], v[158:159], v[36:37]
	v_fmac_f32_e32 v34, v36, v36
	v_mul_f32_e32 v36, v39, v39
	v_lshlrev_b64 v[44:45], 1, v[50:51]
	v_pk_mul_f32 v[50:51], v[156:157], v[32:33]
	v_fmac_f32_e32 v36, v38, v38
	v_mul_f32_e32 v33, v33, v33
	v_add_f32_e32 v34, v34, v36
	v_fmac_f32_e32 v33, v32, v32
	v_add_f32_e32 v32, v34, v33
	v_add_f32_e32 v32, v35, v32
	v_add_f32_e32 v34, v56, v32
	ds_swizzle_b32 v35, v34 offset:swizzle(SWAP,16)
	v_or_b32_e32 v44, 0x100, v44
	v_pk_mul_f32 v[42:43], v[166:167], v[38:39]
	v_lshl_add_u64 v[32:33], s[44:45], 0, v[44:45]
	v_cvt_pk_bf16_f32 v40, v40, v41
	v_cvt_pk_bf16_f32 v41, v42, v43
	v_cvt_pk_bf16_f32 v42, v50, v51
	v_cvt_pk_bf16_f32 v43, v46, v47
	global_store_dwordx4 v[32:33], v[40:43], off
	s_waitcnt lgkmcnt(0)
	v_add_f32_e32 v32, v34, v35
	v_mov_b32_e32 v33, v32
	s_nop 1
	v_permlane32_swap_b32_e32 v32, v33
	s_and_saveexec_b64 s[26:27], s[4:5]
	s_cbranch_execz .LBB0_649
	v_lshl_add_u64 v[34:35], v[48:49], 2, s[50:51]
	v_add_f32_e32 v32, v32, v33
	global_atomic_add_f32 v[34:35], v32, off

.LBB0_650:
	s_nop 0
	v_add_u32_e32 v32, 0xa0, v178
	v_ashrrev_i32_e32 v33, 31, v32
	v_lshlrev_b64 v[34:35], 10, v[32:33]
	v_lshl_add_u64 v[34:35], v[34:35], 0, v[176:177]
	v_lshlrev_b64 v[38:39], 2, v[34:35]
	v_lshl_add_u64 v[36:37], s[10:11], 0, v[38:39]
	global_load_dwordx4 v[40:43], v[36:37], off nt
	global_load_dwordx4 v[44:47], v[36:37], off offset:16 nt
	s_and_b64 vcc, exec, s[8:9]
	v_lshl_add_u64 v[38:39], s[72:73], 0, v[38:39]
	s_waitcnt vmcnt(1)
	v_pk_fma_f32 v[30:31], v[30:31], v[78:79], v[42:43]
	v_pk_fma_f32 v[28:29], v[28:29], v[76:77], v[40:41]
	s_waitcnt vmcnt(0)
	v_pk_fma_f32 v[26:27], v[26:27], v[86:87], v[46:47]
	v_pk_fma_f32 v[24:25], v[24:25], v[84:85], v[44:45]
	v_mov_b32_e32 v40, 0
	global_store_dwordx4 v[38:39], v[28:31], off
	global_store_dwordx4 v[38:39], v[24:27], off offset:16
	s_cbranch_vccnz .LBB0_652
	v_pk_mul_f32 v[40:41], v[30:31], v[30:31]
	v_pk_mul_f32 v[42:43], v[28:29], v[28:29]
	v_pk_mul_f32 v[28:29], v[168:169], v[28:29]
	v_pk_mov_b32 v[44:45], v[42:43], v[40:41] op_sel:[1,0]
	v_mov_b32_e32 v43, v41
	v_pk_add_f32 v[40:41], v[44:45], v[42:43]
	v_pk_mul_f32 v[42:43], v[26:27], v[26:27]
	v_pk_mul_f32 v[44:45], v[24:25], v[24:25]
	v_mov_b32_e32 v46, v42
	v_mov_b32_e32 v47, v44
	v_mov_b32_e32 v44, v43
	v_pk_add_f32 v[42:43], v[46:47], v[44:45]
	v_add_f32_e32 v40, v40, v41
	v_add_f32_e32 v40, v40, v43
	v_add_f32_e32 v40, v42, v40
	v_pk_mul_f32 v[42:43], v[174:175], v[26:27]
	v_pk_mul_f32 v[26:27], v[154:155], v[24:25]
	v_cvt_pk_bf16_f32 v24, v28, v29
	v_lshl_add_u64 v[28:29], v[34:35], 1, s[44:45]
	v_pk_mul_f32 v[30:31], v[170:171], v[30:31]
	s_nop 0
	v_cvt_pk_bf16_f32 v25, v30, v31
	v_cvt_pk_bf16_f32 v26, v26, v27
	v_cvt_pk_bf16_f32 v27, v42, v43
	global_store_dwordx4 v[28:29], v[24:27], off
.LBB0_652:
	global_load_dwordx4 v[24:27], v[36:37], off offset:512 nt
	s_nop 0
	global_load_dwordx4 v[28:31], v[36:37], off offset:528 nt
	s_and_b64 vcc, exec, s[8:9]
	s_waitcnt vmcnt(1)
	v_pk_fma_f32 v[22:23], v[22:23], v[70:71], v[26:27]
	v_pk_fma_f32 v[20:21], v[20:21], v[68:69], v[24:25]
	s_waitcnt vmcnt(0)
	v_pk_fma_f32 v[18:19], v[18:19], v[82:83], v[30:31]
	v_pk_fma_f32 v[16:17], v[16:17], v[80:81], v[28:29]
	global_store_dwordx4 v[38:39], v[20:23], off offset:512
	global_store_dwordx4 v[38:39], v[16:19], off offset:528
	s_cbranch_vccnz .LBB0_656
	v_pk_mul_f32 v[30:31], v[172:173], v[18:19]
	v_mul_f32_e32 v19, v19, v19
	v_fmac_f32_e32 v19, v18, v18
	v_mul_f32_e32 v18, v21, v21
	v_pk_mul_f32 v[24:25], v[158:159], v[20:21]
	v_fmac_f32_e32 v18, v20, v20
	v_mul_f32_e32 v20, v23, v23
	v_lshlrev_b64 v[28:29], 1, v[34:35]
	v_pk_mul_f32 v[34:35], v[156:157], v[16:17]
	v_fmac_f32_e32 v20, v22, v22
	v_mul_f32_e32 v17, v17, v17
	v_add_f32_e32 v18, v18, v20
	v_fmac_f32_e32 v17, v16, v16
	v_add_f32_e32 v16, v18, v17
	v_add_f32_e32 v16, v19, v16
	v_add_f32_e32 v18, v40, v16
	ds_swizzle_b32 v19, v18 offset:swizzle(SWAP,16)
	v_or_b32_e32 v28, 0x100, v28
	v_pk_mul_f32 v[26:27], v[166:167], v[22:23]
	v_lshl_add_u64 v[16:17], s[44:45], 0, v[28:29]
	v_cvt_pk_bf16_f32 v24, v24, v25
	v_cvt_pk_bf16_f32 v25, v26, v27
	v_cvt_pk_bf16_f32 v26, v34, v35
	v_cvt_pk_bf16_f32 v27, v30, v31
	global_store_dwordx4 v[16:17], v[24:27], off
	s_waitcnt lgkmcnt(0)
	v_add_f32_e32 v16, v18, v19
	v_mov_b32_e32 v17, v16
	s_nop 1
	v_permlane32_swap_b32_e32 v16, v17
	s_and_saveexec_b64 s[26:27], s[4:5]
	s_cbranch_execz .LBB0_655
	v_lshl_add_u64 v[18:19], v[32:33], 2, s[50:51]
	v_add_f32_e32 v16, v16, v17
	global_atomic_add_f32 v[18:19], v16, off

.LBB0_656:
	s_nop 0
	v_add_u32_e32 v16, 0xb0, v178
	v_ashrrev_i32_e32 v17, 31, v16
	v_lshlrev_b64 v[18:19], 10, v[16:17]
	v_lshl_add_u64 v[18:19], v[18:19], 0, v[176:177]
	v_lshlrev_b64 v[22:23], 2, v[18:19]
	v_lshl_add_u64 v[20:21], s[10:11], 0, v[22:23]
	global_load_dwordx4 v[24:27], v[20:21], off nt
	global_load_dwordx4 v[28:31], v[20:21], off offset:16 nt
	s_and_b64 vcc, exec, s[8:9]
	v_lshl_add_u64 v[22:23], s[72:73], 0, v[22:23]
	s_waitcnt vmcnt(1)
	v_pk_fma_f32 v[14:15], v[14:15], v[78:79], v[26:27]
	v_pk_fma_f32 v[12:13], v[12:13], v[76:77], v[24:25]
	s_waitcnt vmcnt(0)
	v_pk_fma_f32 v[10:11], v[10:11], v[86:87], v[30:31]
	v_pk_fma_f32 v[8:9], v[8:9], v[84:85], v[28:29]
	v_mov_b32_e32 v24, 0
	global_store_dwordx4 v[22:23], v[12:15], off
	global_store_dwordx4 v[22:23], v[8:11], off offset:16
	s_cbranch_vccnz .LBB0_658
	v_pk_mul_f32 v[24:25], v[14:15], v[14:15]
	v_pk_mul_f32 v[26:27], v[12:13], v[12:13]
	v_pk_mul_f32 v[12:13], v[168:169], v[12:13]
	v_pk_mov_b32 v[28:29], v[26:27], v[24:25] op_sel:[1,0]
	v_mov_b32_e32 v27, v25
	v_pk_add_f32 v[24:25], v[28:29], v[26:27]
	v_pk_mul_f32 v[26:27], v[10:11], v[10:11]
	v_pk_mul_f32 v[28:29], v[8:9], v[8:9]
	v_mov_b32_e32 v30, v26
	v_mov_b32_e32 v31, v28
	v_mov_b32_e32 v28, v27
	v_pk_add_f32 v[26:27], v[30:31], v[28:29]
	v_add_f32_e32 v24, v24, v25
	v_add_f32_e32 v24, v24, v27
	v_add_f32_e32 v24, v26, v24
	v_pk_mul_f32 v[26:27], v[174:175], v[10:11]
	v_pk_mul_f32 v[10:11], v[154:155], v[8:9]
	v_cvt_pk_bf16_f32 v8, v12, v13
	v_lshl_add_u64 v[12:13], v[18:19], 1, s[44:45]
	v_pk_mul_f32 v[14:15], v[170:171], v[14:15]
	s_nop 0
	v_cvt_pk_bf16_f32 v9, v14, v15
	v_cvt_pk_bf16_f32 v10, v10, v11
	v_cvt_pk_bf16_f32 v11, v26, v27
	global_store_dwordx4 v[12:13], v[8:11], off
.LBB0_658:
	global_load_dwordx4 v[8:11], v[20:21], off offset:512 nt
	s_nop 0
	global_load_dwordx4 v[12:15], v[20:21], off offset:528 nt
	s_and_b64 vcc, exec, s[8:9]
	s_waitcnt vmcnt(1)
	v_pk_fma_f32 v[6:7], v[6:7], v[70:71], v[10:11]
	v_pk_fma_f32 v[4:5], v[4:5], v[68:69], v[8:9]
	s_waitcnt vmcnt(0)
	v_pk_fma_f32 v[2:3], v[2:3], v[82:83], v[14:15]
	v_pk_fma_f32 v[0:1], v[0:1], v[80:81], v[12:13]
	global_store_dwordx4 v[22:23], v[4:7], off offset:512
	global_store_dwordx4 v[22:23], v[0:3], off offset:528
	s_cbranch_vccnz .LBB0_662
	v_pk_mul_f32 v[14:15], v[172:173], v[2:3]
	v_mul_f32_e32 v3, v3, v3
	v_fmac_f32_e32 v3, v2, v2
	v_mul_f32_e32 v2, v5, v5
	v_pk_mul_f32 v[8:9], v[158:159], v[4:5]
	v_fmac_f32_e32 v2, v4, v4
	v_mul_f32_e32 v4, v7, v7
	v_lshlrev_b64 v[12:13], 1, v[18:19]
	v_pk_mul_f32 v[18:19], v[156:157], v[0:1]
	v_fmac_f32_e32 v4, v6, v6
	v_mul_f32_e32 v1, v1, v1
	v_add_f32_e32 v2, v2, v4
	v_fmac_f32_e32 v1, v0, v0
	v_add_f32_e32 v0, v2, v1
	v_add_f32_e32 v0, v3, v0
	v_add_f32_e32 v2, v24, v0
	ds_swizzle_b32 v3, v2 offset:swizzle(SWAP,16)
	v_or_b32_e32 v12, 0x100, v12
	v_pk_mul_f32 v[10:11], v[166:167], v[6:7]
	v_lshl_add_u64 v[0:1], s[44:45], 0, v[12:13]
	v_cvt_pk_bf16_f32 v8, v8, v9
	v_cvt_pk_bf16_f32 v9, v10, v11
	v_cvt_pk_bf16_f32 v10, v18, v19
	v_cvt_pk_bf16_f32 v11, v14, v15
	global_store_dwordx4 v[0:1], v[8:11], off
	s_waitcnt lgkmcnt(0)
	v_add_f32_e32 v0, v2, v3
	v_mov_b32_e32 v1, v0
	s_nop 1
	v_permlane32_swap_b32_e32 v0, v1
	s_and_saveexec_b64 s[8:9], s[4:5]
	s_cbranch_execz .LBB0_661
	v_lshl_add_u64 v[2:3], v[16:17], 2, s[50:51]
	v_add_f32_e32 v0, v0, v1
	global_atomic_add_f32 v[2:3], v0, off

.LBB0_804:
	global_load_dwordx4 v[136:139], v[182:183], off offset:512 nt
	s_nop 0
	global_load_dwordx4 v[140:143], v[182:183], off offset:528 nt
	s_and_b64 vcc, exec, s[6:7]
	s_waitcnt vmcnt(1)
	v_pk_fma_f32 v[134:135], v[134:135], v[74:75], v[138:139]
	v_pk_fma_f32 v[132:133], v[132:133], v[72:73], v[136:137]
	s_waitcnt vmcnt(0)
	v_pk_fma_f32 v[130:131], v[130:131], v[82:83], v[142:143]
	v_pk_fma_f32 v[128:129], v[128:129], v[80:81], v[140:141]
	global_store_dwordx4 v[182:183], v[132:135], off offset:512
	global_store_dwordx4 v[182:183], v[128:131], off offset:528
	s_cbranch_vccnz .LBB0_808
	v_pk_mul_f32 v[142:143], v[172:173], v[130:131]
	v_mul_f32_e32 v131, v131, v131
	v_fmac_f32_e32 v131, v130, v130
	v_mul_f32_e32 v130, v133, v133
	v_pk_mul_f32 v[136:137], v[158:159], v[132:133]
	v_fmac_f32_e32 v130, v132, v132
	v_mul_f32_e32 v132, v135, v135
	v_pk_mul_f32 v[162:163], v[154:155], v[128:129]
	v_fmac_f32_e32 v132, v134, v134
	v_mul_f32_e32 v129, v129, v129
	v_add_f32_e32 v130, v130, v132
	v_fmac_f32_e32 v129, v128, v128
	v_add_f32_e32 v128, v130, v129
	v_add_f32_e32 v128, v131, v128
	v_add_f32_e32 v130, v188, v128
	ds_swizzle_b32 v131, v130 offset:swizzle(SWAP,16)
	v_lshlrev_b64 v[140:141], 1, v[180:181]
	v_or_b32_e32 v140, 0x100, v140
	v_pk_mul_f32 v[138:139], v[166:167], v[134:135]
	v_lshl_add_u64 v[128:129], s[44:45], 0, v[140:141]
	v_cvt_pk_bf16_f32 v136, v136, v137
	v_cvt_pk_bf16_f32 v137, v138, v139
	v_cvt_pk_bf16_f32 v138, v162, v163
	v_cvt_pk_bf16_f32 v139, v142, v143
	global_store_dwordx4 v[128:129], v[136:139], off
	s_waitcnt lgkmcnt(0)
	v_add_f32_e32 v128, v130, v131
	v_mov_b32_e32 v129, v128
	s_nop 1
	v_permlane32_swap_b32_e32 v128, v129
	s_and_saveexec_b64 s[24:25], s[2:3]
	s_cbranch_execz .LBB0_807
	v_lshl_add_u64 v[130:131], v[178:179], 2, s[10:11]
	v_add_f32_e32 v128, v128, v129
	global_atomic_add_f32 v[130:131], v128, off

.LBB0_808:
	s_nop 0
	v_or_b32_e32 v128, 16, v178
	v_ashrrev_i32_e32 v129, 31, v128
	v_lshlrev_b64 v[130:131], 10, v[128:129]
	v_lshl_add_u64 v[130:131], v[130:131], 0, v[176:177]
	v_lshl_add_u64 v[132:133], v[130:131], 2, s[72:73]
	global_load_dwordx4 v[134:137], v[132:133], off nt
	global_load_dwordx4 v[138:141], v[132:133], off offset:16 nt
	s_and_b64 vcc, exec, s[6:7]
	s_waitcnt vmcnt(1)
	v_pk_fma_f32 v[126:127], v[126:127], v[78:79], v[136:137]
	v_pk_fma_f32 v[124:125], v[124:125], v[76:77], v[134:135]
	s_waitcnt vmcnt(0)
	v_pk_fma_f32 v[122:123], v[122:123], v[86:87], v[140:141]
	v_pk_fma_f32 v[120:121], v[120:121], v[84:85], v[138:139]
	v_mov_b32_e32 v134, 0
	global_store_dwordx4 v[132:133], v[124:127], off
	global_store_dwordx4 v[132:133], v[120:123], off offset:16
	s_cbranch_vccnz .LBB0_810
	v_pk_mul_f32 v[134:135], v[126:127], v[126:127]
	v_pk_mul_f32 v[136:137], v[124:125], v[124:125]
	v_pk_mul_f32 v[124:125], v[168:169], v[124:125]
	v_pk_mov_b32 v[138:139], v[136:137], v[134:135] op_sel:[1,0]
	v_mov_b32_e32 v137, v135
	v_pk_add_f32 v[134:135], v[138:139], v[136:137]
	v_pk_mul_f32 v[136:137], v[122:123], v[122:123]
	v_pk_mul_f32 v[138:139], v[120:121], v[120:121]
	v_mov_b32_e32 v140, v136
	v_mov_b32_e32 v141, v138
	v_mov_b32_e32 v138, v137
	v_pk_add_f32 v[136:137], v[140:141], v[138:139]
	v_add_f32_e32 v134, v134, v135
	v_add_f32_e32 v134, v134, v137
	v_add_f32_e32 v134, v136, v134
	v_pk_mul_f32 v[136:137], v[174:175], v[122:123]
	v_pk_mul_f32 v[122:123], v[156:157], v[120:121]
	v_cvt_pk_bf16_f32 v120, v124, v125
	v_lshl_add_u64 v[124:125], v[130:131], 1, s[44:45]
	v_pk_mul_f32 v[126:127], v[170:171], v[126:127]
	s_nop 0
	v_cvt_pk_bf16_f32 v121, v126, v127
	v_cvt_pk_bf16_f32 v122, v122, v123
	v_cvt_pk_bf16_f32 v123, v136, v137
	global_store_dwordx4 v[124:125], v[120:123], off
.LBB0_810:
	global_load_dwordx4 v[120:123], v[132:133], off offset:512 nt
	s_nop 0
	global_load_dwordx4 v[124:127], v[132:133], off offset:528 nt
	s_and_b64 vcc, exec, s[6:7]
	s_waitcnt vmcnt(1)
	v_pk_fma_f32 v[118:119], v[118:119], v[74:75], v[122:123]
	v_pk_fma_f32 v[116:117], v[116:117], v[72:73], v[120:121]
	s_waitcnt vmcnt(0)
	v_pk_fma_f32 v[114:115], v[114:115], v[82:83], v[126:127]
	v_pk_fma_f32 v[112:113], v[112:113], v[80:81], v[124:125]
	global_store_dwordx4 v[132:133], v[116:119], off offset:512
	global_store_dwordx4 v[132:133], v[112:115], off offset:528
	s_cbranch_vccnz .LBB0_814
	v_pk_mul_f32 v[126:127], v[172:173], v[114:115]
	v_mul_f32_e32 v115, v115, v115
	v_fmac_f32_e32 v115, v114, v114
	v_mul_f32_e32 v114, v117, v117
	v_pk_mul_f32 v[120:121], v[158:159], v[116:117]
	v_fmac_f32_e32 v114, v116, v116
	v_mul_f32_e32 v116, v119, v119
	v_lshlrev_b64 v[124:125], 1, v[130:131]
	v_pk_mul_f32 v[130:131], v[154:155], v[112:113]
	v_fmac_f32_e32 v116, v118, v118
	v_mul_f32_e32 v113, v113, v113
	v_add_f32_e32 v114, v114, v116
	v_fmac_f32_e32 v113, v112, v112
	v_add_f32_e32 v112, v114, v113
	v_add_f32_e32 v112, v115, v112
	v_add_f32_e32 v114, v134, v112
	ds_swizzle_b32 v115, v114 offset:swizzle(SWAP,16)
	v_or_b32_e32 v124, 0x100, v124
	v_pk_mul_f32 v[122:123], v[166:167], v[118:119]
	v_lshl_add_u64 v[112:113], s[44:45], 0, v[124:125]
	v_cvt_pk_bf16_f32 v120, v120, v121
	v_cvt_pk_bf16_f32 v121, v122, v123
	v_cvt_pk_bf16_f32 v122, v130, v131
	v_cvt_pk_bf16_f32 v123, v126, v127
	global_store_dwordx4 v[112:113], v[120:123], off
	s_waitcnt lgkmcnt(0)
	v_add_f32_e32 v112, v114, v115
	v_mov_b32_e32 v113, v112
	s_nop 1
	v_permlane32_swap_b32_e32 v112, v113
	s_and_saveexec_b64 s[24:25], s[2:3]
	s_cbranch_execz .LBB0_813
	v_lshl_add_u64 v[114:115], v[128:129], 2, s[10:11]
	v_add_f32_e32 v112, v112, v113
	global_atomic_add_f32 v[114:115], v112, off

.LBB0_814:
	s_nop 0
	v_or_b32_e32 v112, 32, v178
	v_ashrrev_i32_e32 v113, 31, v112
	v_lshlrev_b64 v[114:115], 10, v[112:113]
	v_lshl_add_u64 v[114:115], v[114:115], 0, v[176:177]
	v_lshl_add_u64 v[116:117], v[114:115], 2, s[72:73]
	global_load_dwordx4 v[118:121], v[116:117], off nt
	global_load_dwordx4 v[122:125], v[116:117], off offset:16 nt
	s_and_b64 vcc, exec, s[6:7]
	s_waitcnt vmcnt(1)
	v_pk_fma_f32 v[110:111], v[110:111], v[78:79], v[120:121]
	v_pk_fma_f32 v[108:109], v[108:109], v[76:77], v[118:119]
	s_waitcnt vmcnt(0)
	v_pk_fma_f32 v[106:107], v[106:107], v[86:87], v[124:125]
	v_pk_fma_f32 v[104:105], v[104:105], v[84:85], v[122:123]
	v_mov_b32_e32 v118, 0
	global_store_dwordx4 v[116:117], v[108:111], off
	global_store_dwordx4 v[116:117], v[104:107], off offset:16
	s_cbranch_vccnz .LBB0_816
	v_pk_mul_f32 v[118:119], v[110:111], v[110:111]
	v_pk_mul_f32 v[120:121], v[108:109], v[108:109]
	v_pk_mul_f32 v[108:109], v[168:169], v[108:109]
	v_pk_mov_b32 v[122:123], v[120:121], v[118:119] op_sel:[1,0]
	v_mov_b32_e32 v121, v119
	v_pk_add_f32 v[118:119], v[122:123], v[120:121]
	v_pk_mul_f32 v[120:121], v[106:107], v[106:107]
	v_pk_mul_f32 v[122:123], v[104:105], v[104:105]
	v_mov_b32_e32 v124, v120
	v_mov_b32_e32 v125, v122
	v_mov_b32_e32 v122, v121
	v_pk_add_f32 v[120:121], v[124:125], v[122:123]
	v_add_f32_e32 v118, v118, v119
	v_add_f32_e32 v118, v118, v121
	v_add_f32_e32 v118, v120, v118
	v_pk_mul_f32 v[120:121], v[174:175], v[106:107]
	v_pk_mul_f32 v[106:107], v[156:157], v[104:105]
	v_cvt_pk_bf16_f32 v104, v108, v109
	v_lshl_add_u64 v[108:109], v[114:115], 1, s[44:45]
	v_pk_mul_f32 v[110:111], v[170:171], v[110:111]
	s_nop 0
	v_cvt_pk_bf16_f32 v105, v110, v111
	v_cvt_pk_bf16_f32 v106, v106, v107
	v_cvt_pk_bf16_f32 v107, v120, v121
	global_store_dwordx4 v[108:109], v[104:107], off
.LBB0_816:
	global_load_dwordx4 v[104:107], v[116:117], off offset:512 nt
	s_nop 0
	global_load_dwordx4 v[108:111], v[116:117], off offset:528 nt
	s_and_b64 vcc, exec, s[6:7]
	s_waitcnt vmcnt(1)
	v_pk_fma_f32 v[102:103], v[102:103], v[74:75], v[106:107]
	v_pk_fma_f32 v[100:101], v[100:101], v[72:73], v[104:105]
	s_waitcnt vmcnt(0)
	v_pk_fma_f32 v[98:99], v[98:99], v[82:83], v[110:111]
	v_pk_fma_f32 v[96:97], v[96:97], v[80:81], v[108:109]
	global_store_dwordx4 v[116:117], v[100:103], off offset:512
	global_store_dwordx4 v[116:117], v[96:99], off offset:528
	s_cbranch_vccnz .LBB0_820
	v_pk_mul_f32 v[110:111], v[172:173], v[98:99]
	v_mul_f32_e32 v99, v99, v99
	v_fmac_f32_e32 v99, v98, v98
	v_mul_f32_e32 v98, v101, v101
	v_pk_mul_f32 v[104:105], v[158:159], v[100:101]
	v_fmac_f32_e32 v98, v100, v100
	v_mul_f32_e32 v100, v103, v103
	v_lshlrev_b64 v[108:109], 1, v[114:115]
	v_pk_mul_f32 v[114:115], v[154:155], v[96:97]
	v_fmac_f32_e32 v100, v102, v102
	v_mul_f32_e32 v97, v97, v97
	v_add_f32_e32 v98, v98, v100
	v_fmac_f32_e32 v97, v96, v96
	v_add_f32_e32 v96, v98, v97
	v_add_f32_e32 v96, v99, v96
	v_add_f32_e32 v98, v118, v96
	ds_swizzle_b32 v99, v98 offset:swizzle(SWAP,16)
	v_or_b32_e32 v108, 0x100, v108
	v_pk_mul_f32 v[106:107], v[166:167], v[102:103]
	v_lshl_add_u64 v[96:97], s[44:45], 0, v[108:109]
	v_cvt_pk_bf16_f32 v104, v104, v105
	v_cvt_pk_bf16_f32 v105, v106, v107
	v_cvt_pk_bf16_f32 v106, v114, v115
	v_cvt_pk_bf16_f32 v107, v110, v111
	global_store_dwordx4 v[96:97], v[104:107], off
	s_waitcnt lgkmcnt(0)
	v_add_f32_e32 v96, v98, v99
	v_mov_b32_e32 v97, v96
	s_nop 1
	v_permlane32_swap_b32_e32 v96, v97
	s_and_saveexec_b64 s[24:25], s[2:3]
	s_cbranch_execz .LBB0_819
	v_lshl_add_u64 v[98:99], v[112:113], 2, s[10:11]
	v_add_f32_e32 v96, v96, v97
	global_atomic_add_f32 v[98:99], v96, off

.LBB0_820:
	s_nop 0
	v_or_b32_e32 v96, 48, v178
	v_ashrrev_i32_e32 v97, 31, v96
	v_lshlrev_b64 v[98:99], 10, v[96:97]
	v_lshl_add_u64 v[98:99], v[98:99], 0, v[176:177]
	v_lshl_add_u64 v[100:101], v[98:99], 2, s[72:73]
	global_load_dwordx4 v[102:105], v[100:101], off nt
	global_load_dwordx4 v[106:109], v[100:101], off offset:16 nt
	s_and_b64 vcc, exec, s[6:7]
	s_waitcnt vmcnt(1)
	v_pk_fma_f32 v[94:95], v[94:95], v[78:79], v[104:105]
	v_pk_fma_f32 v[92:93], v[92:93], v[76:77], v[102:103]
	s_waitcnt vmcnt(0)
	v_pk_fma_f32 v[90:91], v[90:91], v[86:87], v[108:109]
	v_pk_fma_f32 v[88:89], v[88:89], v[84:85], v[106:107]
	v_mov_b32_e32 v102, 0
	global_store_dwordx4 v[100:101], v[92:95], off
	global_store_dwordx4 v[100:101], v[88:91], off offset:16
	s_cbranch_vccnz .LBB0_822
	v_pk_mul_f32 v[102:103], v[94:95], v[94:95]
	v_pk_mul_f32 v[104:105], v[92:93], v[92:93]
	v_pk_mul_f32 v[92:93], v[168:169], v[92:93]
	v_pk_mov_b32 v[106:107], v[104:105], v[102:103] op_sel:[1,0]
	v_mov_b32_e32 v105, v103
	v_pk_add_f32 v[102:103], v[106:107], v[104:105]
	v_pk_mul_f32 v[104:105], v[90:91], v[90:91]
	v_pk_mul_f32 v[106:107], v[88:89], v[88:89]
	v_mov_b32_e32 v108, v104
	v_mov_b32_e32 v109, v106
	v_mov_b32_e32 v106, v105
	v_pk_add_f32 v[104:105], v[108:109], v[106:107]
	v_add_f32_e32 v102, v102, v103
	v_add_f32_e32 v102, v102, v105
	v_add_f32_e32 v102, v104, v102
	v_pk_mul_f32 v[104:105], v[174:175], v[90:91]
	v_pk_mul_f32 v[90:91], v[156:157], v[88:89]
	v_cvt_pk_bf16_f32 v88, v92, v93
	v_lshl_add_u64 v[92:93], v[98:99], 1, s[44:45]
	v_pk_mul_f32 v[94:95], v[170:171], v[94:95]
	s_nop 0
	v_cvt_pk_bf16_f32 v89, v94, v95
	v_cvt_pk_bf16_f32 v90, v90, v91
	v_cvt_pk_bf16_f32 v91, v104, v105
	global_store_dwordx4 v[92:93], v[88:91], off
.LBB0_822:
	global_load_dwordx4 v[88:91], v[100:101], off offset:512 nt
	s_nop 0
	global_load_dwordx4 v[92:95], v[100:101], off offset:528 nt
	s_and_b64 vcc, exec, s[6:7]
	s_waitcnt vmcnt(1)
	v_pk_fma_f32 v[70:71], v[70:71], v[74:75], v[90:91]
	v_pk_fma_f32 v[68:69], v[68:69], v[72:73], v[88:89]
	s_waitcnt vmcnt(0)
	v_pk_fma_f32 v[66:67], v[66:67], v[82:83], v[94:95]
	v_pk_fma_f32 v[64:65], v[64:65], v[80:81], v[92:93]
	global_store_dwordx4 v[100:101], v[68:71], off offset:512
	global_store_dwordx4 v[100:101], v[64:67], off offset:528
	s_cbranch_vccnz .LBB0_826
	v_pk_mul_f32 v[94:95], v[172:173], v[66:67]
	v_mul_f32_e32 v67, v67, v67
	v_fmac_f32_e32 v67, v66, v66
	v_mul_f32_e32 v66, v69, v69
	v_pk_mul_f32 v[88:89], v[158:159], v[68:69]
	v_fmac_f32_e32 v66, v68, v68
	v_mul_f32_e32 v68, v71, v71
	v_lshlrev_b64 v[92:93], 1, v[98:99]
	v_pk_mul_f32 v[98:99], v[154:155], v[64:65]
	v_fmac_f32_e32 v68, v70, v70
	v_mul_f32_e32 v65, v65, v65
	v_add_f32_e32 v66, v66, v68
	v_fmac_f32_e32 v65, v64, v64
	v_add_f32_e32 v64, v66, v65
	v_add_f32_e32 v64, v67, v64
	v_add_f32_e32 v66, v102, v64
	ds_swizzle_b32 v67, v66 offset:swizzle(SWAP,16)
	v_or_b32_e32 v92, 0x100, v92
	v_pk_mul_f32 v[90:91], v[166:167], v[70:71]
	v_lshl_add_u64 v[64:65], s[44:45], 0, v[92:93]
	v_cvt_pk_bf16_f32 v88, v88, v89
	v_cvt_pk_bf16_f32 v89, v90, v91
	v_cvt_pk_bf16_f32 v90, v98, v99
	v_cvt_pk_bf16_f32 v91, v94, v95
	global_store_dwordx4 v[64:65], v[88:91], off
	s_waitcnt lgkmcnt(0)
	v_add_f32_e32 v64, v66, v67
	v_mov_b32_e32 v65, v64
	s_nop 1
	v_permlane32_swap_b32_e32 v64, v65
	s_and_saveexec_b64 s[24:25], s[2:3]
	s_cbranch_execz .LBB0_825
	v_lshl_add_u64 v[66:67], v[96:97], 2, s[10:11]
	v_add_f32_e32 v64, v64, v65
	global_atomic_add_f32 v[66:67], v64, off

.LBB0_826:
	s_nop 0
	v_add_u32_e32 v64, 0x80, v178
	v_ashrrev_i32_e32 v65, 31, v64
	v_lshlrev_b64 v[66:67], 10, v[64:65]
	v_lshl_add_u64 v[66:67], v[66:67], 0, v[176:177]
	v_lshl_add_u64 v[68:69], v[66:67], 2, s[72:73]
	global_load_dwordx4 v[88:91], v[68:69], off nt
	global_load_dwordx4 v[92:95], v[68:69], off offset:16 nt
	s_and_b64 vcc, exec, s[6:7]
	v_mov_b32_e32 v70, 0
	s_waitcnt vmcnt(1)
	v_pk_fma_f32 v[62:63], v[62:63], v[78:79], v[90:91]
	v_pk_fma_f32 v[60:61], v[60:61], v[76:77], v[88:89]
	s_waitcnt vmcnt(0)
	v_pk_fma_f32 v[58:59], v[58:59], v[86:87], v[94:95]
	v_pk_fma_f32 v[56:57], v[56:57], v[84:85], v[92:93]
	global_store_dwordx4 v[68:69], v[60:63], off
	global_store_dwordx4 v[68:69], v[56:59], off offset:16
	s_cbranch_vccnz .LBB0_828
	v_pk_mul_f32 v[70:71], v[62:63], v[62:63]
	v_pk_mul_f32 v[88:89], v[60:61], v[60:61]
	v_pk_mul_f32 v[60:61], v[168:169], v[60:61]
	v_pk_mov_b32 v[90:91], v[88:89], v[70:71] op_sel:[1,0]
	v_mov_b32_e32 v89, v71
	v_pk_add_f32 v[70:71], v[90:91], v[88:89]
	v_pk_mul_f32 v[88:89], v[58:59], v[58:59]
	v_pk_mul_f32 v[90:91], v[56:57], v[56:57]
	v_mov_b32_e32 v92, v88
	v_mov_b32_e32 v93, v90
	v_mov_b32_e32 v90, v89
	v_pk_add_f32 v[88:89], v[92:93], v[90:91]
	v_add_f32_e32 v70, v70, v71
	v_add_f32_e32 v70, v70, v89
	v_add_f32_e32 v70, v88, v70
	v_pk_mul_f32 v[88:89], v[174:175], v[58:59]
	v_pk_mul_f32 v[58:59], v[156:157], v[56:57]
	v_cvt_pk_bf16_f32 v56, v60, v61
	v_lshl_add_u64 v[60:61], v[66:67], 1, s[44:45]
	v_pk_mul_f32 v[62:63], v[170:171], v[62:63]
	s_nop 0
	v_cvt_pk_bf16_f32 v57, v62, v63
	v_cvt_pk_bf16_f32 v58, v58, v59
	v_cvt_pk_bf16_f32 v59, v88, v89
	global_store_dwordx4 v[60:61], v[56:59], off
.LBB0_828:
	global_load_dwordx4 v[56:59], v[68:69], off offset:512 nt
	s_nop 0
	global_load_dwordx4 v[60:63], v[68:69], off offset:528 nt
	s_and_b64 vcc, exec, s[6:7]
	s_waitcnt vmcnt(1)
	v_pk_fma_f32 v[54:55], v[54:55], v[74:75], v[58:59]
	v_pk_fma_f32 v[52:53], v[52:53], v[72:73], v[56:57]
	s_waitcnt vmcnt(0)
	v_pk_fma_f32 v[50:51], v[50:51], v[82:83], v[62:63]
	v_pk_fma_f32 v[48:49], v[48:49], v[80:81], v[60:61]
	global_store_dwordx4 v[68:69], v[52:55], off offset:512
	global_store_dwordx4 v[68:69], v[48:51], off offset:528
	s_cbranch_vccnz .LBB0_832
	v_pk_mul_f32 v[62:63], v[172:173], v[50:51]
	v_mul_f32_e32 v51, v51, v51
	v_fmac_f32_e32 v51, v50, v50
	v_mul_f32_e32 v50, v53, v53
	v_pk_mul_f32 v[56:57], v[158:159], v[52:53]
	v_fmac_f32_e32 v50, v52, v52
	v_mul_f32_e32 v52, v55, v55
	v_lshlrev_b64 v[60:61], 1, v[66:67]
	v_pk_mul_f32 v[66:67], v[154:155], v[48:49]
	v_fmac_f32_e32 v52, v54, v54
	v_mul_f32_e32 v49, v49, v49
	v_add_f32_e32 v50, v50, v52
	v_fmac_f32_e32 v49, v48, v48
	v_add_f32_e32 v48, v50, v49
	v_add_f32_e32 v48, v51, v48
	v_add_f32_e32 v50, v70, v48
	ds_swizzle_b32 v51, v50 offset:swizzle(SWAP,16)
	v_or_b32_e32 v60, 0x100, v60
	v_pk_mul_f32 v[58:59], v[166:167], v[54:55]
	v_lshl_add_u64 v[48:49], s[44:45], 0, v[60:61]
	v_cvt_pk_bf16_f32 v56, v56, v57
	v_cvt_pk_bf16_f32 v57, v58, v59
	v_cvt_pk_bf16_f32 v58, v66, v67
	v_cvt_pk_bf16_f32 v59, v62, v63
	global_store_dwordx4 v[48:49], v[56:59], off
	s_waitcnt lgkmcnt(0)
	v_add_f32_e32 v48, v50, v51
	v_mov_b32_e32 v49, v48
	s_nop 1
	v_permlane32_swap_b32_e32 v48, v49
	s_and_saveexec_b64 s[24:25], s[2:3]
	s_cbranch_execz .LBB0_831
	v_lshl_add_u64 v[50:51], v[64:65], 2, s[10:11]
	v_add_f32_e32 v48, v48, v49
	global_atomic_add_f32 v[50:51], v48, off

.LBB0_832:
	s_nop 0
	v_add_u32_e32 v48, 0x90, v178
	v_ashrrev_i32_e32 v49, 31, v48
	v_lshlrev_b64 v[50:51], 10, v[48:49]
	v_lshl_add_u64 v[50:51], v[50:51], 0, v[176:177]
	v_lshl_add_u64 v[52:53], v[50:51], 2, s[72:73]
	global_load_dwordx4 v[54:57], v[52:53], off nt
	global_load_dwordx4 v[58:61], v[52:53], off offset:16 nt
	s_and_b64 vcc, exec, s[6:7]
	s_waitcnt vmcnt(1)
	v_pk_fma_f32 v[46:47], v[46:47], v[78:79], v[56:57]
	v_pk_fma_f32 v[44:45], v[44:45], v[76:77], v[54:55]
	s_waitcnt vmcnt(0)
	v_pk_fma_f32 v[42:43], v[42:43], v[86:87], v[60:61]
	v_pk_fma_f32 v[40:41], v[40:41], v[84:85], v[58:59]
	v_mov_b32_e32 v54, 0
	global_store_dwordx4 v[52:53], v[44:47], off
	global_store_dwordx4 v[52:53], v[40:43], off offset:16
	s_cbranch_vccnz .LBB0_834
	v_pk_mul_f32 v[54:55], v[46:47], v[46:47]
	v_pk_mul_f32 v[56:57], v[44:45], v[44:45]
	v_pk_mul_f32 v[44:45], v[168:169], v[44:45]
	v_pk_mov_b32 v[58:59], v[56:57], v[54:55] op_sel:[1,0]
	v_mov_b32_e32 v57, v55
	v_pk_add_f32 v[54:55], v[58:59], v[56:57]
	v_pk_mul_f32 v[56:57], v[42:43], v[42:43]
	v_pk_mul_f32 v[58:59], v[40:41], v[40:41]
	v_mov_b32_e32 v60, v56
	v_mov_b32_e32 v61, v58
	v_mov_b32_e32 v58, v57
	v_pk_add_f32 v[56:57], v[60:61], v[58:59]
	v_add_f32_e32 v54, v54, v55
	v_add_f32_e32 v54, v54, v57
	v_add_f32_e32 v54, v56, v54
	v_pk_mul_f32 v[56:57], v[174:175], v[42:43]
	v_pk_mul_f32 v[42:43], v[156:157], v[40:41]
	v_cvt_pk_bf16_f32 v40, v44, v45
	v_lshl_add_u64 v[44:45], v[50:51], 1, s[44:45]
	v_pk_mul_f32 v[46:47], v[170:171], v[46:47]
	s_nop 0
	v_cvt_pk_bf16_f32 v41, v46, v47
	v_cvt_pk_bf16_f32 v42, v42, v43
	v_cvt_pk_bf16_f32 v43, v56, v57
	global_store_dwordx4 v[44:45], v[40:43], off
.LBB0_834:
	global_load_dwordx4 v[40:43], v[52:53], off offset:512 nt
	s_nop 0
	global_load_dwordx4 v[44:47], v[52:53], off offset:528 nt
	s_and_b64 vcc, exec, s[6:7]
	s_waitcnt vmcnt(1)
	v_pk_fma_f32 v[38:39], v[38:39], v[74:75], v[42:43]
	v_pk_fma_f32 v[36:37], v[36:37], v[72:73], v[40:41]
	s_waitcnt vmcnt(0)
	v_pk_fma_f32 v[34:35], v[34:35], v[82:83], v[46:47]
	v_pk_fma_f32 v[32:33], v[32:33], v[80:81], v[44:45]
	global_store_dwordx4 v[52:53], v[36:39], off offset:512
	global_store_dwordx4 v[52:53], v[32:35], off offset:528
	s_cbranch_vccnz .LBB0_838
	v_pk_mul_f32 v[46:47], v[172:173], v[34:35]
	v_mul_f32_e32 v35, v35, v35
	v_fmac_f32_e32 v35, v34, v34
	v_mul_f32_e32 v34, v37, v37
	v_pk_mul_f32 v[40:41], v[158:159], v[36:37]
	v_fmac_f32_e32 v34, v36, v36
	v_mul_f32_e32 v36, v39, v39
	v_lshlrev_b64 v[44:45], 1, v[50:51]
	v_pk_mul_f32 v[50:51], v[154:155], v[32:33]
	v_fmac_f32_e32 v36, v38, v38
	v_mul_f32_e32 v33, v33, v33
	v_add_f32_e32 v34, v34, v36
	v_fmac_f32_e32 v33, v32, v32
	v_add_f32_e32 v32, v34, v33
	v_add_f32_e32 v32, v35, v32
	v_add_f32_e32 v34, v54, v32
	ds_swizzle_b32 v35, v34 offset:swizzle(SWAP,16)
	v_or_b32_e32 v44, 0x100, v44
	v_pk_mul_f32 v[42:43], v[166:167], v[38:39]
	v_lshl_add_u64 v[32:33], s[44:45], 0, v[44:45]
	v_cvt_pk_bf16_f32 v40, v40, v41
	v_cvt_pk_bf16_f32 v41, v42, v43
	v_cvt_pk_bf16_f32 v42, v50, v51
	v_cvt_pk_bf16_f32 v43, v46, v47
	global_store_dwordx4 v[32:33], v[40:43], off
	s_waitcnt lgkmcnt(0)
	v_add_f32_e32 v32, v34, v35
	v_mov_b32_e32 v33, v32
	s_nop 1
	v_permlane32_swap_b32_e32 v32, v33
	s_and_saveexec_b64 s[24:25], s[2:3]
	s_cbranch_execz .LBB0_837
	v_lshl_add_u64 v[34:35], v[48:49], 2, s[10:11]
	v_add_f32_e32 v32, v32, v33
	global_atomic_add_f32 v[34:35], v32, off

.LBB0_838:
	s_nop 0
	v_add_u32_e32 v32, 0xa0, v178
	v_ashrrev_i32_e32 v33, 31, v32
	v_lshlrev_b64 v[34:35], 10, v[32:33]
	v_lshl_add_u64 v[34:35], v[34:35], 0, v[176:177]
	v_lshl_add_u64 v[36:37], v[34:35], 2, s[72:73]
	global_load_dwordx4 v[38:41], v[36:37], off nt
	global_load_dwordx4 v[42:45], v[36:37], off offset:16 nt
	s_and_b64 vcc, exec, s[6:7]
	s_waitcnt vmcnt(1)
	v_pk_fma_f32 v[30:31], v[30:31], v[78:79], v[40:41]
	v_pk_fma_f32 v[28:29], v[28:29], v[76:77], v[38:39]
	s_waitcnt vmcnt(0)
	v_pk_fma_f32 v[26:27], v[26:27], v[86:87], v[44:45]
	v_pk_fma_f32 v[24:25], v[24:25], v[84:85], v[42:43]
	v_mov_b32_e32 v38, 0
	global_store_dwordx4 v[36:37], v[28:31], off
	global_store_dwordx4 v[36:37], v[24:27], off offset:16
	s_cbranch_vccnz .LBB0_840
	v_pk_mul_f32 v[38:39], v[30:31], v[30:31]
	v_pk_mul_f32 v[40:41], v[28:29], v[28:29]
	v_pk_mul_f32 v[28:29], v[168:169], v[28:29]
	v_pk_mov_b32 v[42:43], v[40:41], v[38:39] op_sel:[1,0]
	v_mov_b32_e32 v41, v39
	v_pk_add_f32 v[38:39], v[42:43], v[40:41]
	v_pk_mul_f32 v[40:41], v[26:27], v[26:27]
	v_pk_mul_f32 v[42:43], v[24:25], v[24:25]
	v_mov_b32_e32 v44, v40
	v_mov_b32_e32 v45, v42
	v_mov_b32_e32 v42, v41
	v_pk_add_f32 v[40:41], v[44:45], v[42:43]
	v_add_f32_e32 v38, v38, v39
	v_add_f32_e32 v38, v38, v41
	v_add_f32_e32 v38, v40, v38
	v_pk_mul_f32 v[40:41], v[174:175], v[26:27]
	v_pk_mul_f32 v[26:27], v[156:157], v[24:25]
	v_cvt_pk_bf16_f32 v24, v28, v29
	v_lshl_add_u64 v[28:29], v[34:35], 1, s[44:45]
	v_pk_mul_f32 v[30:31], v[170:171], v[30:31]
	s_nop 0
	v_cvt_pk_bf16_f32 v25, v30, v31
	v_cvt_pk_bf16_f32 v26, v26, v27
	v_cvt_pk_bf16_f32 v27, v40, v41
	global_store_dwordx4 v[28:29], v[24:27], off
.LBB0_840:
	global_load_dwordx4 v[24:27], v[36:37], off offset:512 nt
	s_nop 0
	global_load_dwordx4 v[28:31], v[36:37], off offset:528 nt
	s_and_b64 vcc, exec, s[6:7]
	s_waitcnt vmcnt(1)
	v_pk_fma_f32 v[22:23], v[22:23], v[74:75], v[26:27]
	v_pk_fma_f32 v[20:21], v[20:21], v[72:73], v[24:25]
	s_waitcnt vmcnt(0)
	v_pk_fma_f32 v[18:19], v[18:19], v[82:83], v[30:31]
	v_pk_fma_f32 v[16:17], v[16:17], v[80:81], v[28:29]
	global_store_dwordx4 v[36:37], v[20:23], off offset:512
	global_store_dwordx4 v[36:37], v[16:19], off offset:528
	s_cbranch_vccnz .LBB0_844
	v_pk_mul_f32 v[30:31], v[172:173], v[18:19]
	v_mul_f32_e32 v19, v19, v19
	v_fmac_f32_e32 v19, v18, v18
	v_mul_f32_e32 v18, v21, v21
	v_pk_mul_f32 v[24:25], v[158:159], v[20:21]
	v_fmac_f32_e32 v18, v20, v20
	v_mul_f32_e32 v20, v23, v23
	v_lshlrev_b64 v[28:29], 1, v[34:35]
	v_pk_mul_f32 v[34:35], v[154:155], v[16:17]
	v_fmac_f32_e32 v20, v22, v22
	v_mul_f32_e32 v17, v17, v17
	v_add_f32_e32 v18, v18, v20
	v_fmac_f32_e32 v17, v16, v16
	v_add_f32_e32 v16, v18, v17
	v_add_f32_e32 v16, v19, v16
	v_add_f32_e32 v18, v38, v16
	ds_swizzle_b32 v19, v18 offset:swizzle(SWAP,16)
	v_or_b32_e32 v28, 0x100, v28
	v_pk_mul_f32 v[26:27], v[166:167], v[22:23]
	v_lshl_add_u64 v[16:17], s[44:45], 0, v[28:29]
	v_cvt_pk_bf16_f32 v24, v24, v25
	v_cvt_pk_bf16_f32 v25, v26, v27
	v_cvt_pk_bf16_f32 v26, v34, v35
	v_cvt_pk_bf16_f32 v27, v30, v31
	global_store_dwordx4 v[16:17], v[24:27], off
	s_waitcnt lgkmcnt(0)
	v_add_f32_e32 v16, v18, v19
	v_mov_b32_e32 v17, v16
	s_nop 1
	v_permlane32_swap_b32_e32 v16, v17
	s_and_saveexec_b64 s[24:25], s[2:3]
	s_cbranch_execz .LBB0_843
	v_lshl_add_u64 v[18:19], v[32:33], 2, s[10:11]
	v_add_f32_e32 v16, v16, v17
	global_atomic_add_f32 v[18:19], v16, off

.LBB0_844:
	s_nop 0
	v_add_u32_e32 v16, 0xb0, v178
	v_ashrrev_i32_e32 v17, 31, v16
	v_lshlrev_b64 v[18:19], 10, v[16:17]
	v_lshl_add_u64 v[18:19], v[18:19], 0, v[176:177]
	v_lshl_add_u64 v[20:21], v[18:19], 2, s[72:73]
	global_load_dwordx4 v[22:25], v[20:21], off nt
	global_load_dwordx4 v[26:29], v[20:21], off offset:16 nt
	s_and_b64 vcc, exec, s[6:7]
	s_waitcnt vmcnt(1)
	v_pk_fma_f32 v[14:15], v[14:15], v[78:79], v[24:25]
	v_pk_fma_f32 v[12:13], v[12:13], v[76:77], v[22:23]
	s_waitcnt vmcnt(0)
	v_pk_fma_f32 v[10:11], v[10:11], v[86:87], v[28:29]
	v_pk_fma_f32 v[8:9], v[8:9], v[84:85], v[26:27]
	v_mov_b32_e32 v22, 0
	global_store_dwordx4 v[20:21], v[12:15], off
	global_store_dwordx4 v[20:21], v[8:11], off offset:16
	s_cbranch_vccnz .LBB0_846
	v_pk_mul_f32 v[22:23], v[14:15], v[14:15]
	v_pk_mul_f32 v[24:25], v[12:13], v[12:13]
	v_pk_mul_f32 v[12:13], v[168:169], v[12:13]
	v_pk_mov_b32 v[26:27], v[24:25], v[22:23] op_sel:[1,0]
	v_mov_b32_e32 v25, v23
	v_pk_add_f32 v[22:23], v[26:27], v[24:25]
	v_pk_mul_f32 v[24:25], v[10:11], v[10:11]
	v_pk_mul_f32 v[26:27], v[8:9], v[8:9]
	v_mov_b32_e32 v28, v24
	v_mov_b32_e32 v29, v26
	v_mov_b32_e32 v26, v25
	v_pk_add_f32 v[24:25], v[28:29], v[26:27]
	v_add_f32_e32 v22, v22, v23
	v_add_f32_e32 v22, v22, v25
	v_add_f32_e32 v22, v24, v22
	v_pk_mul_f32 v[24:25], v[174:175], v[10:11]
	v_pk_mul_f32 v[10:11], v[156:157], v[8:9]
	v_cvt_pk_bf16_f32 v8, v12, v13
	v_lshl_add_u64 v[12:13], v[18:19], 1, s[44:45]
	v_pk_mul_f32 v[14:15], v[170:171], v[14:15]
	s_nop 0
	v_cvt_pk_bf16_f32 v9, v14, v15
	v_cvt_pk_bf16_f32 v10, v10, v11
	v_cvt_pk_bf16_f32 v11, v24, v25
	global_store_dwordx4 v[12:13], v[8:11], off
.LBB0_846:
	global_load_dwordx4 v[8:11], v[20:21], off offset:512 nt
	s_nop 0
	global_load_dwordx4 v[12:15], v[20:21], off offset:528 nt
	s_and_b64 vcc, exec, s[6:7]
	s_waitcnt vmcnt(1)
	v_pk_fma_f32 v[6:7], v[6:7], v[74:75], v[10:11]
	v_pk_fma_f32 v[4:5], v[4:5], v[72:73], v[8:9]
	s_waitcnt vmcnt(0)
	v_pk_fma_f32 v[2:3], v[2:3], v[82:83], v[14:15]
	v_pk_fma_f32 v[0:1], v[0:1], v[80:81], v[12:13]
	global_store_dwordx4 v[20:21], v[4:7], off offset:512
	global_store_dwordx4 v[20:21], v[0:3], off offset:528
	s_cbranch_vccnz .LBB0_850
	v_pk_mul_f32 v[14:15], v[172:173], v[2:3]
	v_mul_f32_e32 v3, v3, v3
	v_fmac_f32_e32 v3, v2, v2
	v_mul_f32_e32 v2, v5, v5
	v_pk_mul_f32 v[8:9], v[158:159], v[4:5]
	v_fmac_f32_e32 v2, v4, v4
	v_mul_f32_e32 v4, v7, v7
	v_lshlrev_b64 v[12:13], 1, v[18:19]
	v_pk_mul_f32 v[18:19], v[154:155], v[0:1]
	v_fmac_f32_e32 v4, v6, v6
	v_mul_f32_e32 v1, v1, v1
	v_add_f32_e32 v2, v2, v4
	v_fmac_f32_e32 v1, v0, v0
	v_add_f32_e32 v0, v2, v1
	v_add_f32_e32 v0, v3, v0
	v_add_f32_e32 v2, v22, v0
	ds_swizzle_b32 v3, v2 offset:swizzle(SWAP,16)
	v_or_b32_e32 v12, 0x100, v12
	v_pk_mul_f32 v[10:11], v[166:167], v[6:7]
	v_lshl_add_u64 v[0:1], s[44:45], 0, v[12:13]
	v_cvt_pk_bf16_f32 v8, v8, v9
	v_cvt_pk_bf16_f32 v9, v10, v11
	v_cvt_pk_bf16_f32 v10, v18, v19
	v_cvt_pk_bf16_f32 v11, v14, v15
	global_store_dwordx4 v[0:1], v[8:11], off
	s_waitcnt lgkmcnt(0)
	v_add_f32_e32 v0, v2, v3
	v_mov_b32_e32 v1, v0
	s_nop 1
	v_permlane32_swap_b32_e32 v0, v1
	s_and_saveexec_b64 s[6:7], s[2:3]
	s_cbranch_execz .LBB0_849
	v_lshl_add_u64 v[2:3], v[16:17], 2, s[10:11]
	v_add_f32_e32 v0, v0, v1
	global_atomic_add_f32 v[2:3], v0, off
